# MLA attention: LDS K/V fragment reads prefetched into spare VGPRs, counted vmcnt on K/V staging
# speedup vs baseline: 1.0123x; 1.0123x over previous
.LBB0_1445:
	s_add_i32 s22, s93, 0xffffff81
	s_cmp_gt_i32 s22, s91
	s_cbranch_scc1 .LBB0_1451
	v_add_u32_e32 v96, v141, v126
	ds_read_b128 v[192:195], v96 offset:0
	ds_read_b128 v[196:199], v96 offset:32
	ds_read_b128 v[200:203], v96 offset:64
	ds_read_b128 v[204:207], v96 offset:96
	ds_read_b128 v[208:211], v96 offset:128
	ds_read_b128 v[212:215], v96 offset:160
	ds_read_b128 v[216:219], v96 offset:6656
	ds_read_b128 v[162:165], v96 offset:6688
	ds_read_b128 v[166:169], v96 offset:6720
	ds_read_b128 v[170:173], v96 offset:6752
	ds_read_b128 v[174:177], v96 offset:6784
	ds_read_b128 v[178:181], v96 offset:6816
	v_xor_b32_e32 v32, 0x80000000, v148
	v_mov_b32_e32 v33, v32
	v_mov_b32_e32 v34, v32
	v_mov_b32_e32 v35, v32
	v_mov_b32_e32 v36, v32
	v_mov_b32_e32 v37, v32
	v_mov_b32_e32 v38, v32
	v_mov_b32_e32 v39, v32
	v_mov_b32_e32 v40, v32
	v_mov_b32_e32 v41, v32
	v_mov_b32_e32 v42, v32
	v_mov_b32_e32 v43, v32
	v_mov_b32_e32 v44, v32
	v_mov_b32_e32 v45, v32
	v_mov_b32_e32 v46, v32
	v_mov_b32_e32 v47, v32
	v_add_u32_e32 v182, v143, v144
	v_add_u32_e32 v183, 0x3000, v182
	v_add_u32_e32 v184, 0x4000, v182
	v_xor_b32_e32 v185, 32, v225
	v_lshlrev_b32_e32 v185, 2, v185
	s_sub_i32 s22, s93, 64
	s_cmp_le_i32 s22, s90
	s_waitcnt lgkmcnt(11)
	v_mfma_f32_32x32x16_bf16 v[48:63], v[192:195], v[80:83], v[32:47]
	ds_read2_b64 v[192:195], v183 offset0:128 offset1:130
	s_waitcnt lgkmcnt(11)
	v_mfma_f32_32x32x16_bf16 v[48:63], v[196:199], v[84:87], v[48:63]
	ds_read2_b64 v[196:199], v184 offset0:160 offset1:162
	s_waitcnt lgkmcnt(11)
	v_mfma_f32_32x32x16_bf16 v[48:63], v[200:203], v[88:91], v[48:63]
	ds_read2_b64 v[200:203], v183 offset0:132 offset1:134
	s_waitcnt lgkmcnt(11)
	v_mfma_f32_32x32x16_bf16 v[48:63], v[204:207], v[92:95], v[48:63]
	ds_read2_b64 v[204:207], v184 offset0:164 offset1:166
	s_waitcnt lgkmcnt(11)
	v_mfma_f32_32x32x16_bf16 v[48:63], v[208:211], v[100:103], v[48:63]
	ds_read2_b64 v[208:211], v183 offset0:136 offset1:138
	s_waitcnt lgkmcnt(11)
	v_mfma_f32_32x32x16_bf16 v[48:63], v[212:215], v[104:107], v[48:63]
	ds_read2_b64 v[212:215], v184 offset0:168 offset1:170
	s_waitcnt lgkmcnt(11)
	v_mfma_f32_32x32x16_bf16 v[32:47], v[216:219], v[80:83], v[32:47]
	ds_read2_b64 v[216:219], v183 offset0:140 offset1:142
	s_waitcnt lgkmcnt(11)
	v_mfma_f32_32x32x16_bf16 v[32:47], v[162:165], v[84:87], v[32:47]
	ds_read2_b64 v[162:165], v184 offset0:172 offset1:174
	s_waitcnt lgkmcnt(11)
	v_mfma_f32_32x32x16_bf16 v[32:47], v[166:169], v[88:91], v[32:47]
	s_waitcnt lgkmcnt(10)
	v_mfma_f32_32x32x16_bf16 v[32:47], v[170:173], v[92:95], v[32:47]
	s_waitcnt lgkmcnt(9)
	v_mfma_f32_32x32x16_bf16 v[32:47], v[174:177], v[100:103], v[32:47]
	s_waitcnt lgkmcnt(8)
	v_mfma_f32_32x32x16_bf16 v[32:47], v[178:181], v[104:107], v[32:47]
	s_cbranch_scc1 .LBB0_1448
	v_add_u32_e32 v96, s93, v140
	v_add_u32_e32 v99, 0xffffffa1, v96
	v_add_u32_e32 v98, 0xffffff81, v96
	v_cmp_le_i32_e32 vcc, v99, v142
	s_nop 6
	v_cndmask_b32_e32 v32, v235, v32, vcc
	v_cmp_lt_i32_e32 vcc, v98, v142
	s_nop 1
	v_cndmask_b32_e32 v49, v235, v49, vcc
	v_cmp_le_i32_e32 vcc, v98, v142
	v_add_u32_e32 v98, 0xffffffa2, v96
	s_nop 0
	v_cndmask_b32_e32 v48, v235, v48, vcc
	v_cmp_le_i32_e32 vcc, v98, v142
	v_add_u32_e32 v98, 0xffffff83, v96
	s_nop 0
	v_cndmask_b32_e32 v33, v235, v33, vcc
	v_cmp_le_i32_e32 vcc, v98, v142
	v_add_u32_e32 v98, 0xffffffa3, v96
	s_nop 0
	v_cndmask_b32_e32 v50, v235, v50, vcc
	v_cmp_le_i32_e32 vcc, v98, v142
	v_add_u32_e32 v98, 0xffffff84, v96
	s_nop 0
	v_cndmask_b32_e32 v34, v235, v34, vcc
	v_cmp_le_i32_e32 vcc, v98, v142
	v_add_u32_e32 v98, 0xffffffa4, v96
	s_nop 0
	v_cndmask_b32_e32 v51, v235, v51, vcc
	v_cmp_le_i32_e32 vcc, v98, v142
	v_add_u32_e32 v98, 0xffffff89, v96
	s_nop 0
	v_cndmask_b32_e32 v35, v235, v35, vcc
	v_cmp_le_i32_e32 vcc, v98, v142
	v_add_u32_e32 v98, 0xffffffa9, v96
	s_nop 0
	v_cndmask_b32_e32 v52, v235, v52, vcc
	v_cmp_le_i32_e32 vcc, v98, v142
	v_add_u32_e32 v98, 0xffffff8a, v96
	s_nop 0
	v_cndmask_b32_e32 v36, v235, v36, vcc
	v_cmp_le_i32_e32 vcc, v98, v142
	v_add_u32_e32 v98, 0xffffffaa, v96
	s_nop 0
	v_cndmask_b32_e32 v53, v235, v53, vcc
	v_cmp_le_i32_e32 vcc, v98, v142
	v_add_u32_e32 v98, 0xffffff8b, v96
	s_nop 0
	v_cndmask_b32_e32 v37, v235, v37, vcc
	v_cmp_le_i32_e32 vcc, v98, v142
	v_add_u32_e32 v98, 0xffffffab, v96
	s_nop 0
	v_cndmask_b32_e32 v54, v235, v54, vcc
	v_cmp_le_i32_e32 vcc, v98, v142
	v_add_u32_e32 v98, 0xffffff8c, v96
	s_nop 0
	v_cndmask_b32_e32 v38, v235, v38, vcc
	v_cmp_le_i32_e32 vcc, v98, v142
	v_add_u32_e32 v98, 0xffffffac, v96
	s_nop 0
	v_cndmask_b32_e32 v55, v235, v55, vcc
	v_cmp_le_i32_e32 vcc, v98, v142
	v_add_u32_e32 v98, 0xffffff91, v96
	s_nop 0
	v_cndmask_b32_e32 v39, v235, v39, vcc
	v_cmp_le_i32_e32 vcc, v98, v142
	v_add_u32_e32 v98, 0xffffffb1, v96
	s_nop 0
	v_cndmask_b32_e32 v56, v235, v56, vcc
	v_cmp_le_i32_e32 vcc, v98, v142
	v_add_u32_e32 v98, 0xffffff92, v96
	s_nop 0
	v_cndmask_b32_e32 v40, v235, v40, vcc
	v_cmp_le_i32_e32 vcc, v98, v142
	v_add_u32_e32 v98, 0xffffffb2, v96
	s_nop 0
	v_cndmask_b32_e32 v57, v235, v57, vcc
	v_cmp_le_i32_e32 vcc, v98, v142
	v_add_u32_e32 v98, 0xffffff93, v96
	s_nop 0
	v_cndmask_b32_e32 v41, v235, v41, vcc
	v_cmp_le_i32_e32 vcc, v98, v142
	v_add_u32_e32 v98, 0xffffffb3, v96
	s_nop 0
	v_cndmask_b32_e32 v58, v235, v58, vcc
	v_cmp_le_i32_e32 vcc, v98, v142
	v_add_u32_e32 v98, 0xffffff94, v96
	s_nop 0
	v_cndmask_b32_e32 v42, v235, v42, vcc
	v_cmp_le_i32_e32 vcc, v98, v142
	v_add_u32_e32 v98, 0xffffffb4, v96
	s_nop 0
	v_cndmask_b32_e32 v59, v235, v59, vcc
	v_cmp_le_i32_e32 vcc, v98, v142
	v_add_u32_e32 v98, 0xffffff99, v96
	s_nop 0
	v_cndmask_b32_e32 v43, v235, v43, vcc
	v_cmp_le_i32_e32 vcc, v98, v142
	v_add_u32_e32 v98, 0xffffffb9, v96
	s_nop 0
	v_cndmask_b32_e32 v60, v235, v60, vcc
	v_cmp_le_i32_e32 vcc, v98, v142
	v_add_u32_e32 v98, 0xffffff9a, v96
	s_nop 0
	v_cndmask_b32_e32 v44, v235, v44, vcc
	v_cmp_le_i32_e32 vcc, v98, v142
	v_add_u32_e32 v98, 0xffffffba, v96
	s_nop 0
	v_cndmask_b32_e32 v61, v235, v61, vcc
	v_cmp_le_i32_e32 vcc, v98, v142
	v_add_u32_e32 v98, 0xffffff9b, v96
	s_nop 0
	v_cndmask_b32_e32 v45, v235, v45, vcc
	v_cmp_le_i32_e32 vcc, v98, v142
	v_add_u32_e32 v98, 0xffffffbb, v96
	s_nop 0
	v_cndmask_b32_e32 v62, v235, v62, vcc
	v_cmp_le_i32_e32 vcc, v98, v142
	v_add_u32_e32 v98, 0xffffff9c, v96
	v_add_u32_e32 v96, 0xffffffbc, v96
	v_cndmask_b32_e32 v46, v235, v46, vcc
	v_cmp_le_i32_e32 vcc, v98, v142
	s_nop 1
	v_cndmask_b32_e32 v63, v235, v63, vcc
	v_cmp_le_i32_e32 vcc, v96, v142
	s_nop 1
	v_cndmask_b32_e32 v47, v235, v47, vcc
.LBB0_1448:
	s_nop 10
	v_max3_f32 v96, v48, v49, v50
	v_max3_f32 v98, v32, v33, v34
	v_max3_f32 v96, v96, v51, v52
	v_max3_f32 v98, v98, v35, v36
	v_max3_f32 v96, v96, v53, v54
	v_max3_f32 v98, v98, v37, v38
	v_max3_f32 v96, v96, v55, v56
	v_max3_f32 v98, v98, v39, v40
	v_max3_f32 v96, v96, v57, v58
	v_max3_f32 v98, v98, v41, v42
	v_max3_f32 v96, v96, v59, v60
	v_max3_f32 v98, v98, v43, v44
	v_max3_f32 v96, v96, v61, v62
	v_max3_f32 v98, v98, v45, v46
	v_max3_f32 v96, v96, v98, v63
	v_max_f32_e32 v96, v96, v47
	ds_bpermute_b32 v98, v185, v96
	s_waitcnt lgkmcnt(0)
	v_max_f32_e32 v96, v96, v98
	v_cmp_lt_f32_e32 vcc, s20, v96
	s_cbranch_vccz .LBB0_1450
	v_max_f32_e32 v96, v96, v96
	v_max_f32_e32 v96, 0, v96
	v_exp_f32_e64 v98, -v96
	v_add_f32_e32 v148, v148, v96
	v_pk_add_f32 v[48:49], v[48:49], v[96:97] op_sel_hi:[1,0] neg_lo:[0,1] neg_hi:[0,1]
	v_pk_add_f32 v[32:33], v[32:33], v[96:97] op_sel_hi:[1,0] neg_lo:[0,1] neg_hi:[0,1]
	v_mul_f32_e32 v129, v129, v98
	v_pk_add_f32 v[50:51], v[50:51], v[96:97] op_sel_hi:[1,0] neg_lo:[0,1] neg_hi:[0,1]
	v_pk_add_f32 v[34:35], v[34:35], v[96:97] op_sel_hi:[1,0] neg_lo:[0,1] neg_hi:[0,1]
	v_pk_add_f32 v[52:53], v[52:53], v[96:97] op_sel_hi:[1,0] neg_lo:[0,1] neg_hi:[0,1]
	v_pk_add_f32 v[36:37], v[36:37], v[96:97] op_sel_hi:[1,0] neg_lo:[0,1] neg_hi:[0,1]
	v_pk_add_f32 v[54:55], v[54:55], v[96:97] op_sel_hi:[1,0] neg_lo:[0,1] neg_hi:[0,1]
	v_pk_add_f32 v[38:39], v[38:39], v[96:97] op_sel_hi:[1,0] neg_lo:[0,1] neg_hi:[0,1]
	v_pk_add_f32 v[56:57], v[56:57], v[96:97] op_sel_hi:[1,0] neg_lo:[0,1] neg_hi:[0,1]
	v_pk_add_f32 v[40:41], v[40:41], v[96:97] op_sel_hi:[1,0] neg_lo:[0,1] neg_hi:[0,1]
	v_pk_add_f32 v[58:59], v[58:59], v[96:97] op_sel_hi:[1,0] neg_lo:[0,1] neg_hi:[0,1]
	v_pk_add_f32 v[42:43], v[42:43], v[96:97] op_sel_hi:[1,0] neg_lo:[0,1] neg_hi:[0,1]
	v_pk_add_f32 v[60:61], v[60:61], v[96:97] op_sel_hi:[1,0] neg_lo:[0,1] neg_hi:[0,1]
	v_pk_add_f32 v[44:45], v[44:45], v[96:97] op_sel_hi:[1,0] neg_lo:[0,1] neg_hi:[0,1]
	v_pk_add_f32 v[62:63], v[62:63], v[96:97] op_sel_hi:[1,0] neg_lo:[0,1] neg_hi:[0,1]
	v_pk_add_f32 v[46:47], v[46:47], v[96:97] op_sel_hi:[1,0] neg_lo:[0,1] neg_hi:[0,1]
	v_pk_mul_f32 v[30:31], v[30:31], v[98:99] op_sel_hi:[1,0]
	v_pk_mul_f32 v[28:29], v[28:29], v[98:99] op_sel_hi:[1,0]
	v_pk_mul_f32 v[26:27], v[26:27], v[98:99] op_sel_hi:[1,0]
	v_pk_mul_f32 v[24:25], v[24:25], v[98:99] op_sel_hi:[1,0]
	v_pk_mul_f32 v[22:23], v[22:23], v[98:99] op_sel_hi:[1,0]
	v_pk_mul_f32 v[20:21], v[20:21], v[98:99] op_sel_hi:[1,0]
	v_pk_mul_f32 v[18:19], v[18:19], v[98:99] op_sel_hi:[1,0]
	v_pk_mul_f32 v[16:17], v[16:17], v[98:99] op_sel_hi:[1,0]
	v_pk_mul_f32 v[14:15], v[14:15], v[98:99] op_sel_hi:[1,0]
	v_pk_mul_f32 v[12:13], v[12:13], v[98:99] op_sel_hi:[1,0]
	v_pk_mul_f32 v[10:11], v[10:11], v[98:99] op_sel_hi:[1,0]
	v_pk_mul_f32 v[8:9], v[8:9], v[98:99] op_sel_hi:[1,0]
	v_pk_mul_f32 v[6:7], v[6:7], v[98:99] op_sel_hi:[1,0]
	v_pk_mul_f32 v[4:5], v[4:5], v[98:99] op_sel_hi:[1,0]
	v_pk_mul_f32 v[2:3], v[2:3], v[98:99] op_sel_hi:[1,0]
	v_pk_mul_f32 v[0:1], v[0:1], v[98:99] op_sel_hi:[1,0]
.LBB0_1450:
	v_exp_f32_e32 v48, v48
	v_exp_f32_e32 v49, v49
	v_exp_f32_e32 v50, v50
	v_exp_f32_e32 v51, v51
	v_exp_f32_e32 v52, v52
	v_exp_f32_e32 v53, v53
	v_exp_f32_e32 v54, v54
	v_exp_f32_e32 v55, v55
	v_exp_f32_e32 v56, v56
	v_exp_f32_e32 v57, v57
	v_exp_f32_e32 v58, v58
	v_exp_f32_e32 v59, v59
	v_exp_f32_e32 v60, v60
	v_exp_f32_e32 v61, v61
	v_exp_f32_e32 v62, v62
	v_exp_f32_e32 v63, v63
	v_exp_f32_e32 v32, v32
	v_exp_f32_e32 v33, v33
	v_exp_f32_e32 v34, v34
	v_exp_f32_e32 v35, v35
	v_exp_f32_e32 v36, v36
	v_exp_f32_e32 v37, v37
	v_exp_f32_e32 v38, v38
	v_exp_f32_e32 v39, v39
	v_exp_f32_e32 v40, v40
	v_exp_f32_e32 v41, v41
	v_exp_f32_e32 v42, v42
	v_exp_f32_e32 v43, v43
	v_exp_f32_e32 v44, v44
	v_exp_f32_e32 v45, v45
	v_exp_f32_e32 v46, v46
	v_exp_f32_e32 v47, v47
	v_add_f32_e32 v149, v48, v49
	v_add_f32_e32 v150, v56, v57
	v_add_f32_e32 v151, v32, v33
	v_add_f32_e32 v152, v40, v41
	v_add_f32_e32 v149, v149, v50
	v_add_f32_e32 v150, v150, v58
	v_add_f32_e32 v151, v151, v34
	v_add_f32_e32 v152, v152, v42
	v_add_f32_e32 v149, v149, v51
	v_add_f32_e32 v150, v150, v59
	v_add_f32_e32 v151, v151, v35
	v_add_f32_e32 v152, v152, v43
	v_add_f32_e32 v149, v149, v52
	v_add_f32_e32 v150, v150, v60
	v_add_f32_e32 v151, v151, v36
	v_add_f32_e32 v152, v152, v44
	v_add_f32_e32 v149, v149, v53
	v_add_f32_e32 v150, v150, v61
	v_add_f32_e32 v151, v151, v37
	v_add_f32_e32 v152, v152, v45
	v_add_f32_e32 v149, v149, v54
	v_add_f32_e32 v150, v150, v62
	v_add_f32_e32 v151, v151, v38
	v_add_f32_e32 v152, v152, v46
	v_add_f32_e32 v149, v149, v55
	v_add_f32_e32 v150, v150, v63
	v_add_f32_e32 v151, v151, v39
	v_add_f32_e32 v152, v152, v47
	v_cvt_pk_bf16_f32 v236, v48, v49
	v_cvt_pk_bf16_f32 v237, v50, v51
	v_cvt_pk_bf16_f32 v238, v52, v53
	v_cvt_pk_bf16_f32 v239, v54, v55
	v_cvt_pk_bf16_f32 v240, v56, v57
	v_cvt_pk_bf16_f32 v241, v58, v59
	v_cvt_pk_bf16_f32 v242, v60, v61
	v_cvt_pk_bf16_f32 v243, v62, v63
	v_cvt_pk_bf16_f32 v244, v32, v33
	v_cvt_pk_bf16_f32 v245, v34, v35
	v_cvt_pk_bf16_f32 v246, v36, v37
	v_cvt_pk_bf16_f32 v247, v38, v39
	v_cvt_pk_bf16_f32 v186, v40, v41
	v_cvt_pk_bf16_f32 v187, v42, v43
	v_cvt_pk_bf16_f32 v188, v44, v45
	v_cvt_pk_bf16_f32 v189, v46, v47
	v_add_f32_e32 v149, v149, v150
	v_add_f32_e32 v151, v151, v152
	v_add_f32_e32 v149, v149, v151
	v_add_f32_e32 v129, v129, v149
	v_mfma_f32_32x32x16_bf16 v[16:31], v[192:195], v[236:239], v[16:31]
	v_mfma_f32_32x32x16_bf16 v[0:15], v[196:199], v[236:239], v[0:15]
	v_mfma_f32_32x32x16_bf16 v[16:31], v[200:203], v[240:243], v[16:31]
	v_mfma_f32_32x32x16_bf16 v[0:15], v[204:207], v[240:243], v[0:15]
	v_mfma_f32_32x32x16_bf16 v[16:31], v[208:211], v[244:247], v[16:31]
	v_mfma_f32_32x32x16_bf16 v[0:15], v[212:215], v[244:247], v[0:15]
	v_mfma_f32_32x32x16_bf16 v[16:31], v[216:219], v[186:189], v[16:31]
	v_mfma_f32_32x32x16_bf16 v[0:15], v[162:165], v[186:189], v[0:15]
.LBB0_1451:
	s_add_i32 s22, s92, -2
	s_cmp_lt_u32 s22, s89
	s_cselect_b64 s[72:73], -1, 0
	s_cmp_ge_u32 s22, s89
	s_cbranch_scc1 .LBB0_1457
	s_and_b64 vcc, exec, s[70:71]
	s_cbranch_vccz .Lmla_wA1_old
	s_waitcnt vmcnt(3)
	s_branch .Lmla_wA1_done

.Lmla_wA1_done:
	ds_write_b128 v127, v[72:75] offset:22016
	s_and_saveexec_b64 s[74:75], s[8:9]
	v_add_u32_e32 v32, v145, v137
	ds_write_b128 v32, v[64:67] offset:22016
	s_or_b64 exec, exec, s[74:75]
	v_add3_u32 v32, v138, v128, s21
	s_and_b64 vcc, exec, s[70:71]
	s_cbranch_vccz .Lmla_wA2_nob
	s_and_b64 vcc, exec, s[8:9]
	s_cbranch_vccz .Lmla_wA2_w47
	s_waitcnt vmcnt(3)
	s_branch .Lmla_wA2_done
.Lmla_wA2_w47:
	s_waitcnt vmcnt(2)
	s_branch .Lmla_wA2_done

.Lmla_wA2_done:
	ds_write2_b64 v32, v[76:77], v[78:79] offset1:1
	s_and_saveexec_b64 s[74:75], s[10:11]
	v_add3_u32 v32, v146, v147, s21
	ds_write2_b64 v32, v[68:69], v[70:71] offset1:1
	s_or_b64 exec, exec, s[74:75]

.LBB0_1466:
	v_add_u32_e32 v96, v141, v126
	ds_read_b128 v[192:195], v96 offset:22016
	ds_read_b128 v[196:199], v96 offset:22048
	ds_read_b128 v[200:203], v96 offset:22080
	ds_read_b128 v[204:207], v96 offset:22112
	ds_read_b128 v[208:211], v96 offset:22144
	ds_read_b128 v[212:215], v96 offset:22176
	ds_read_b128 v[216:219], v96 offset:28672
	ds_read_b128 v[162:165], v96 offset:28704
	ds_read_b128 v[166:169], v96 offset:28736
	ds_read_b128 v[170:173], v96 offset:28768
	ds_read_b128 v[174:177], v96 offset:28800
	ds_read_b128 v[178:181], v96 offset:28832
	v_xor_b32_e32 v32, 0x80000000, v148
	v_mov_b32_e32 v33, v32
	v_mov_b32_e32 v34, v32
	v_mov_b32_e32 v35, v32
	v_mov_b32_e32 v36, v32
	v_mov_b32_e32 v37, v32
	v_mov_b32_e32 v38, v32
	v_mov_b32_e32 v39, v32
	v_mov_b32_e32 v40, v32
	v_mov_b32_e32 v41, v32
	v_mov_b32_e32 v42, v32
	v_mov_b32_e32 v43, v32
	v_mov_b32_e32 v44, v32
	v_mov_b32_e32 v45, v32
	v_mov_b32_e32 v46, v32
	v_mov_b32_e32 v47, v32
	v_add_u32_e32 v182, v143, v144
	v_add_u32_e32 v183, 0x8800, v182
	v_add_u32_e32 v184, 0x9800, v182
	v_xor_b32_e32 v185, 32, v225
	v_lshlrev_b32_e32 v185, 2, v185
	s_cmp_le_i32 s93, s90
	s_waitcnt lgkmcnt(11)
	v_mfma_f32_32x32x16_bf16 v[48:63], v[192:195], v[80:83], v[32:47]
	ds_read2_b64 v[192:195], v183 offset0:64 offset1:66
	s_waitcnt lgkmcnt(11)
	v_mfma_f32_32x32x16_bf16 v[48:63], v[196:199], v[84:87], v[48:63]
	ds_read2_b64 v[196:199], v184 offset0:96 offset1:98
	s_waitcnt lgkmcnt(11)
	v_mfma_f32_32x32x16_bf16 v[48:63], v[200:203], v[88:91], v[48:63]
	ds_read2_b64 v[200:203], v183 offset0:68 offset1:70
	s_waitcnt lgkmcnt(11)
	v_mfma_f32_32x32x16_bf16 v[48:63], v[204:207], v[92:95], v[48:63]
	ds_read2_b64 v[204:207], v184 offset0:100 offset1:102
	s_waitcnt lgkmcnt(11)
	v_mfma_f32_32x32x16_bf16 v[48:63], v[208:211], v[100:103], v[48:63]
	ds_read2_b64 v[208:211], v183 offset0:72 offset1:74
	s_waitcnt lgkmcnt(11)
	v_mfma_f32_32x32x16_bf16 v[48:63], v[212:215], v[104:107], v[48:63]
	ds_read2_b64 v[212:215], v184 offset0:104 offset1:106
	s_waitcnt lgkmcnt(11)
	v_mfma_f32_32x32x16_bf16 v[32:47], v[216:219], v[80:83], v[32:47]
	ds_read2_b64 v[216:219], v183 offset0:76 offset1:78
	s_waitcnt lgkmcnt(11)
	v_mfma_f32_32x32x16_bf16 v[32:47], v[162:165], v[84:87], v[32:47]
	ds_read2_b64 v[162:165], v184 offset0:108 offset1:110
	s_waitcnt lgkmcnt(11)
	v_mfma_f32_32x32x16_bf16 v[32:47], v[166:169], v[88:91], v[32:47]
	s_waitcnt lgkmcnt(10)
	v_mfma_f32_32x32x16_bf16 v[32:47], v[170:173], v[92:95], v[32:47]
	s_waitcnt lgkmcnt(9)
	v_mfma_f32_32x32x16_bf16 v[32:47], v[174:177], v[100:103], v[32:47]
	s_waitcnt lgkmcnt(8)
	v_mfma_f32_32x32x16_bf16 v[32:47], v[178:181], v[104:107], v[32:47]
	s_cbranch_scc1 .LBB0_1468
	v_add_u32_e32 v96, s93, v140
	v_subrev_u32_e32 v99, 31, v96
	v_subrev_u32_e32 v98, 63, v96
	v_cmp_le_i32_e32 vcc, v99, v142
	s_nop 6
	v_cndmask_b32_e32 v32, v235, v32, vcc
	v_cmp_lt_i32_e32 vcc, v98, v142
	s_nop 1
	v_cndmask_b32_e32 v49, v235, v49, vcc
	v_cmp_le_i32_e32 vcc, v98, v142
	v_subrev_u32_e32 v98, 30, v96
	s_nop 0
	v_cndmask_b32_e32 v48, v235, v48, vcc
	v_cmp_le_i32_e32 vcc, v98, v142
	v_subrev_u32_e32 v98, 61, v96
	s_nop 0
	v_cndmask_b32_e32 v33, v235, v33, vcc
	v_cmp_le_i32_e32 vcc, v98, v142
	v_subrev_u32_e32 v98, 29, v96
	s_nop 0
	v_cndmask_b32_e32 v50, v235, v50, vcc
	v_cmp_le_i32_e32 vcc, v98, v142
	v_subrev_u32_e32 v98, 60, v96
	s_nop 0
	v_cndmask_b32_e32 v34, v235, v34, vcc
	v_cmp_le_i32_e32 vcc, v98, v142
	v_subrev_u32_e32 v98, 28, v96
	s_nop 0
	v_cndmask_b32_e32 v51, v235, v51, vcc
	v_cmp_le_i32_e32 vcc, v98, v142
	v_subrev_u32_e32 v98, 55, v96
	s_nop 0
	v_cndmask_b32_e32 v35, v235, v35, vcc
	v_cmp_le_i32_e32 vcc, v98, v142
	v_subrev_u32_e32 v98, 23, v96
	s_nop 0
	v_cndmask_b32_e32 v52, v235, v52, vcc
	v_cmp_le_i32_e32 vcc, v98, v142
	v_subrev_u32_e32 v98, 54, v96
	s_nop 0
	v_cndmask_b32_e32 v36, v235, v36, vcc
	v_cmp_le_i32_e32 vcc, v98, v142
	v_subrev_u32_e32 v98, 22, v96
	s_nop 0
	v_cndmask_b32_e32 v53, v235, v53, vcc
	v_cmp_le_i32_e32 vcc, v98, v142
	v_subrev_u32_e32 v98, 53, v96
	s_nop 0
	v_cndmask_b32_e32 v37, v235, v37, vcc
	v_cmp_le_i32_e32 vcc, v98, v142
	v_subrev_u32_e32 v98, 21, v96
	s_nop 0
	v_cndmask_b32_e32 v54, v235, v54, vcc
	v_cmp_le_i32_e32 vcc, v98, v142
	v_subrev_u32_e32 v98, 52, v96
	s_nop 0
	v_cndmask_b32_e32 v38, v235, v38, vcc
	v_cmp_le_i32_e32 vcc, v98, v142
	v_subrev_u32_e32 v98, 20, v96
	s_nop 0
	v_cndmask_b32_e32 v55, v235, v55, vcc
	v_cmp_le_i32_e32 vcc, v98, v142
	v_subrev_u32_e32 v98, 47, v96
	s_nop 0
	v_cndmask_b32_e32 v39, v235, v39, vcc
	v_cmp_le_i32_e32 vcc, v98, v142
	v_add_u32_e32 v98, -15, v96
	s_nop 0
	v_cndmask_b32_e32 v56, v235, v56, vcc
	v_cmp_le_i32_e32 vcc, v98, v142
	v_subrev_u32_e32 v98, 46, v96
	s_nop 0
	v_cndmask_b32_e32 v40, v235, v40, vcc
	v_cmp_le_i32_e32 vcc, v98, v142
	v_add_u32_e32 v98, -14, v96
	s_nop 0
	v_cndmask_b32_e32 v57, v235, v57, vcc
	v_cmp_le_i32_e32 vcc, v98, v142
	v_subrev_u32_e32 v98, 45, v96
	s_nop 0
	v_cndmask_b32_e32 v41, v235, v41, vcc
	v_cmp_le_i32_e32 vcc, v98, v142
	v_add_u32_e32 v98, -13, v96
	s_nop 0
	v_cndmask_b32_e32 v58, v235, v58, vcc
	v_cmp_le_i32_e32 vcc, v98, v142
	v_subrev_u32_e32 v98, 44, v96
	s_nop 0
	v_cndmask_b32_e32 v42, v235, v42, vcc
	v_cmp_le_i32_e32 vcc, v98, v142
	v_add_u32_e32 v98, -12, v96
	s_nop 0
	v_cndmask_b32_e32 v59, v235, v59, vcc
	v_cmp_le_i32_e32 vcc, v98, v142
	v_subrev_u32_e32 v98, 39, v96
	s_nop 0
	v_cndmask_b32_e32 v43, v235, v43, vcc
	v_cmp_le_i32_e32 vcc, v98, v142
	v_add_u32_e32 v98, -7, v96
	s_nop 0
	v_cndmask_b32_e32 v60, v235, v60, vcc
	v_cmp_le_i32_e32 vcc, v98, v142
	v_subrev_u32_e32 v98, 38, v96
	s_nop 0
	v_cndmask_b32_e32 v44, v235, v44, vcc
	v_cmp_le_i32_e32 vcc, v98, v142
	v_add_u32_e32 v98, -6, v96
	s_nop 0
	v_cndmask_b32_e32 v61, v235, v61, vcc
	v_cmp_le_i32_e32 vcc, v98, v142
	v_subrev_u32_e32 v98, 37, v96
	s_nop 0
	v_cndmask_b32_e32 v45, v235, v45, vcc
	v_cmp_le_i32_e32 vcc, v98, v142
	v_add_u32_e32 v98, -5, v96
	s_nop 0
	v_cndmask_b32_e32 v62, v235, v62, vcc
	v_cmp_le_i32_e32 vcc, v98, v142
	v_subrev_u32_e32 v98, 36, v96
	v_add_u32_e32 v96, -4, v96
	v_cndmask_b32_e32 v46, v235, v46, vcc
	v_cmp_le_i32_e32 vcc, v98, v142
	s_nop 1
	v_cndmask_b32_e32 v63, v235, v63, vcc
	v_cmp_le_i32_e32 vcc, v96, v142
	s_nop 1
	v_cndmask_b32_e32 v47, v235, v47, vcc

.LBB0_1470:
	v_exp_f32_e32 v48, v48
	v_exp_f32_e32 v49, v49
	v_exp_f32_e32 v50, v50
	v_exp_f32_e32 v51, v51
	v_exp_f32_e32 v52, v52
	v_exp_f32_e32 v53, v53
	v_exp_f32_e32 v54, v54
	v_exp_f32_e32 v55, v55
	v_exp_f32_e32 v56, v56
	v_exp_f32_e32 v57, v57
	v_exp_f32_e32 v58, v58
	v_exp_f32_e32 v59, v59
	v_exp_f32_e32 v60, v60
	v_exp_f32_e32 v61, v61
	v_exp_f32_e32 v62, v62
	v_exp_f32_e32 v63, v63
	v_exp_f32_e32 v32, v32
	v_exp_f32_e32 v33, v33
	v_exp_f32_e32 v34, v34
	v_exp_f32_e32 v35, v35
	v_exp_f32_e32 v36, v36
	v_exp_f32_e32 v37, v37
	v_exp_f32_e32 v38, v38
	v_exp_f32_e32 v39, v39
	v_exp_f32_e32 v40, v40
	v_exp_f32_e32 v41, v41
	v_exp_f32_e32 v42, v42
	v_exp_f32_e32 v43, v43
	v_exp_f32_e32 v44, v44
	v_exp_f32_e32 v45, v45
	v_exp_f32_e32 v46, v46
	v_exp_f32_e32 v47, v47
	v_add_f32_e32 v149, v48, v49
	v_add_f32_e32 v150, v56, v57
	v_add_f32_e32 v151, v32, v33
	v_add_f32_e32 v152, v40, v41
	v_add_f32_e32 v149, v149, v50
	v_add_f32_e32 v150, v150, v58
	v_add_f32_e32 v151, v151, v34
	v_add_f32_e32 v152, v152, v42
	v_add_f32_e32 v149, v149, v51
	v_add_f32_e32 v150, v150, v59
	v_add_f32_e32 v151, v151, v35
	v_add_f32_e32 v152, v152, v43
	v_add_f32_e32 v149, v149, v52
	v_add_f32_e32 v150, v150, v60
	v_add_f32_e32 v151, v151, v36
	v_add_f32_e32 v152, v152, v44
	v_add_f32_e32 v149, v149, v53
	v_add_f32_e32 v150, v150, v61
	v_add_f32_e32 v151, v151, v37
	v_add_f32_e32 v152, v152, v45
	v_add_f32_e32 v149, v149, v54
	v_add_f32_e32 v150, v150, v62
	v_add_f32_e32 v151, v151, v38
	v_add_f32_e32 v152, v152, v46
	v_add_f32_e32 v149, v149, v55
	v_add_f32_e32 v150, v150, v63
	v_add_f32_e32 v151, v151, v39
	v_add_f32_e32 v152, v152, v47
	v_cvt_pk_bf16_f32 v236, v48, v49
	v_cvt_pk_bf16_f32 v237, v50, v51
	v_cvt_pk_bf16_f32 v238, v52, v53
	v_cvt_pk_bf16_f32 v239, v54, v55
	v_cvt_pk_bf16_f32 v240, v56, v57
	v_cvt_pk_bf16_f32 v241, v58, v59
	v_cvt_pk_bf16_f32 v242, v60, v61
	v_cvt_pk_bf16_f32 v243, v62, v63
	v_cvt_pk_bf16_f32 v244, v32, v33
	v_cvt_pk_bf16_f32 v245, v34, v35
	v_cvt_pk_bf16_f32 v246, v36, v37
	v_cvt_pk_bf16_f32 v247, v38, v39
	v_cvt_pk_bf16_f32 v186, v40, v41
	v_cvt_pk_bf16_f32 v187, v42, v43
	v_cvt_pk_bf16_f32 v188, v44, v45
	v_cvt_pk_bf16_f32 v189, v46, v47
	v_add_f32_e32 v149, v149, v150
	v_add_f32_e32 v151, v151, v152
	v_add_f32_e32 v149, v149, v151
	v_add_f32_e32 v129, v129, v149
	v_mfma_f32_32x32x16_bf16 v[16:31], v[192:195], v[236:239], v[16:31]
	v_mfma_f32_32x32x16_bf16 v[0:15], v[196:199], v[236:239], v[0:15]
	v_mfma_f32_32x32x16_bf16 v[16:31], v[200:203], v[240:243], v[16:31]
	v_mfma_f32_32x32x16_bf16 v[0:15], v[204:207], v[240:243], v[0:15]
	v_mfma_f32_32x32x16_bf16 v[16:31], v[208:211], v[244:247], v[16:31]
	v_mfma_f32_32x32x16_bf16 v[0:15], v[212:215], v[244:247], v[0:15]
	v_mfma_f32_32x32x16_bf16 v[16:31], v[216:219], v[186:189], v[16:31]
	v_mfma_f32_32x32x16_bf16 v[0:15], v[162:165], v[186:189], v[0:15]
	s_andn2_b64 vcc, exec, s[70:71]
	s_cbranch_vccnz .LBB0_1437
.LBB0_1471:
	s_cmp_lt_u32 s92, s89
	s_cbranch_scc0 .Lmla_wB1_old
	s_waitcnt vmcnt(3)
	s_branch .Lmla_wB1_done

.Lmla_wB1_done:
	ds_write_b128 v127, v[108:111]
	s_and_saveexec_b64 s[70:71], s[8:9]
	v_add_u32_e32 v32, v145, v137
	ds_write_b128 v32, v[116:119]
	s_or_b64 exec, exec, s[70:71]
	s_cmp_lt_u32 s92, s89
	s_cbranch_scc0 .Lmla_wB2_nob
	s_and_b64 vcc, exec, s[8:9]
	s_cbranch_vccz .Lmla_wB2_w47
	s_waitcnt vmcnt(3)
	s_branch .Lmla_wB2_done

.Lmla_wB2_done:
	ds_write2_b64 v139, v[120:121], v[122:123] offset1:1
	s_and_saveexec_b64 s[70:71], s[10:11]
	s_cbranch_execz .LBB0_1436
	v_add3_u32 v32, v146, v147, s2
	ds_write2_b64 v32, v[112:113], v[114:115] offset1:1
	s_branch .LBB0_1436
